# gn row loop: current<-next register moves gathered behind the last store under vmcnt(8); early full vmcnt wait and header store-drain wait removed
# baseline (speedup 1.0000x reference)
.LBB0_735:
	s_or_b64 exec, exec, s[4:5]
	v_ashrrev_i32_e32 v0, 6, v24
	v_add_u32_e32 v64, s85, v0
	s_movk_i32 s0, 0x2000
	v_cmp_gt_i32_e32 vcc, s0, v64
	s_waitcnt lgkmcnt(0)
	s_barrier
	s_and_saveexec_b64 s[4:5], vcc
	s_cbranch_execz .LBB0_740
	s_add_u32 s8, s6, 0x26800000
	s_addc_u32 s9, s7, 0
	s_add_u32 s14, s6, 0x2a800000
	s_addc_u32 s15, s7, 0
	v_and_b32_e32 v20, 63, v24
	s_add_u32 s10, s6, 0x1e000000
	v_ashrrev_i32_e32 v65, 31, v64
	s_addc_u32 s11, s7, 0
	v_lshlrev_b64 v[0:1], 11, v[64:65]
	v_lshlrev_b32_e32 v66, 2, v20
	v_lshlrev_b64 v[4:5], 7, v[64:65]
	v_lshrrev_b32_e32 v2, 2, v24
	s_add_u32 s12, s6, 0x14000000
	v_mov_b32_e32 v3, 0
	v_or_b32_e32 v0, v0, v66
	v_lshl_add_u64 v[4:5], s[14:15], 0, v[4:5]
	v_and_b32_e32 v2, 12, v2
	s_addc_u32 s13, s7, 0
	v_lshl_add_u64 v[8:9], v[4:5], 0, v[2:3]
	v_lshl_add_u64 v[4:5], v[0:1], 2, s[8:9]
	v_lshlrev_b64 v[6:7], 1, v[0:1]
	v_lshl_add_u64 v[10:11], s[10:11], 0, v[6:7]
	global_load_dwordx4 v[60:63], v[4:5], off
	global_load_dwordx2 v[122:123], v[10:11], off
	v_lshl_add_u64 v[4:5], s[12:13], 0, v[6:7]
	v_or_b32_e32 v6, 0x100, v0
	v_mov_b32_e32 v7, v1
	v_lshl_add_u64 v[10:11], v[6:7], 2, s[8:9]
	global_load_dwordx2 v[116:117], v[4:5], off
	global_load_dwordx4 v[56:59], v[10:11], off
	v_lshlrev_b64 v[4:5], 1, v[6:7]
	v_lshl_add_u64 v[6:7], s[10:11], 0, v[4:5]
	v_lshl_add_u64 v[4:5], s[12:13], 0, v[4:5]
	global_load_dwordx2 v[126:127], v[6:7], off
	global_load_dwordx2 v[118:119], v[4:5], off
	v_or_b32_e32 v4, 0x200, v0
	v_mov_b32_e32 v5, v1
	v_lshl_add_u64 v[6:7], v[4:5], 2, s[8:9]
	v_lshlrev_b64 v[4:5], 1, v[4:5]
	v_lshl_add_u64 v[10:11], s[10:11], 0, v[4:5]
	global_load_dwordx4 v[52:55], v[6:7], off
	global_load_dwordx2 v[132:133], v[10:11], off
	v_lshl_add_u64 v[4:5], s[12:13], 0, v[4:5]
	v_or_b32_e32 v6, 0x300, v0
	v_mov_b32_e32 v7, v1
	v_lshl_add_u64 v[10:11], v[6:7], 2, s[8:9]
	global_load_dwordx2 v[128:129], v[4:5], off
	global_load_dwordx4 v[48:51], v[10:11], off
	v_lshlrev_b64 v[4:5], 1, v[6:7]
	v_lshl_add_u64 v[6:7], s[10:11], 0, v[4:5]
	v_lshl_add_u64 v[4:5], s[12:13], 0, v[4:5]
	global_load_dwordx2 v[138:139], v[6:7], off
	global_load_dwordx2 v[130:131], v[4:5], off
	v_or_b32_e32 v4, 0x400, v0
	v_mov_b32_e32 v5, v1
	v_lshl_add_u64 v[6:7], v[4:5], 2, s[8:9]
	v_lshlrev_b64 v[4:5], 1, v[4:5]
	v_lshl_add_u64 v[10:11], s[10:11], 0, v[4:5]
	v_lshl_add_u64 v[4:5], s[12:13], 0, v[4:5]
	global_load_dwordx2 v[136:137], v[4:5], off
	v_or_b32_e32 v4, 0x500, v0
	v_mov_b32_e32 v5, v1
	v_lshlrev_b64 v[12:13], 1, v[4:5]
	v_lshl_add_u64 v[14:15], s[10:11], 0, v[12:13]
	v_lshl_add_u64 v[12:13], s[12:13], 0, v[12:13]
	global_load_dwordx2 v[146:147], v[14:15], off
	global_load_dwordx2 v[140:141], v[12:13], off
	v_or_b32_e32 v12, 0x600, v0
	v_mov_b32_e32 v13, v1
	v_lshlrev_b64 v[14:15], 1, v[12:13]
	v_lshl_add_u64 v[16:17], s[12:13], 0, v[14:15]
	v_or_b32_e32 v0, 0x700, v0
	global_load_dwordx2 v[144:145], v[16:17], off
	v_lshlrev_b64 v[16:17], 1, v[0:1]
	v_lshl_add_u64 v[18:19], s[10:11], 0, v[16:17]
	v_lshl_add_u64 v[4:5], v[4:5], 2, s[8:9]
	v_lshl_add_u64 v[16:17], s[12:13], 0, v[16:17]
	global_load_dwordx2 v[148:149], v[18:19], off
	global_load_dwordx2 v[120:121], v[16:17], off
	global_load_dwordx4 v[44:47], v[6:7], off
	global_load_dwordx2 v[142:143], v[10:11], off
	global_load_dwordx4 v[40:43], v[4:5], off
	v_lshl_add_u64 v[4:5], v[12:13], 2, s[8:9]
	v_lshl_add_u64 v[6:7], s[10:11], 0, v[14:15]
	global_load_dwordx4 v[28:31], v[4:5], off
	global_load_dwordx2 v[150:151], v[6:7], off
	v_lshl_add_u64 v[0:1], v[0:1], 2, s[8:9]
	global_load_dwordx4 v[4:7], v[0:1], off
	global_load_dword v134, v[8:9], off
	global_load_dword v124, v[8:9], off offset:16
	global_load_dword v114, v[8:9], off offset:32
	global_load_dword v112, v[8:9], off offset:48
	global_load_dword v110, v[8:9], off offset:64
	global_load_dword v108, v[8:9], off offset:80
	global_load_dword v90, v[8:9], off offset:96
	global_load_dword v72, v[8:9], off offset:112
	v_lshlrev_b64 v[0:1], 12, v[64:65]
	v_lshl_or_b32 v0, v20, 3, v0
	v_lshl_add_u64 v[0:1], s[6:7], 0, v[0:1]
	s_mov_b64 s[6:7], 0x2a900000
	v_lshl_add_u64 v[68:69], s[14:15], 0, v[2:3]
	v_lshl_add_u32 v67, v20, 4, 0
	v_lshl_add_u64 v[70:71], v[0:1], 0, s[6:7]
	s_ashr_i32 s43, s42, 31
	s_lshl_b64 s[14:15], s[42:43], 12
	s_mov_b64 s[16:17], 0
	s_movk_i32 s1, 0x1fff
	v_mov_b32_e32 v73, 0x3a27c5ac
	s_mov_b32 s3, 0x800000
	s_waitcnt vmcnt(31)
	v_mov_b64_e32 v[0:1], v[60:61]
	s_waitcnt vmcnt(30)
	v_mov_b64_e32 v[76:77], v[122:123]
	v_mov_b64_e32 v[2:3], v[62:63]
	s_waitcnt vmcnt(29)
	v_mov_b64_e32 v[74:75], v[116:117]
	s_waitcnt vmcnt(28)
	v_mov_b64_e32 v[8:9], v[56:57]
	v_mov_b64_e32 v[10:11], v[58:59]
	s_waitcnt vmcnt(27)
	v_mov_b64_e32 v[80:81], v[126:127]
	s_waitcnt vmcnt(26)
	v_mov_b64_e32 v[78:79], v[118:119]
	s_waitcnt vmcnt(25)
	v_mov_b64_e32 v[12:13], v[52:53]
	s_waitcnt vmcnt(24)
	v_mov_b64_e32 v[84:85], v[132:133]
	v_mov_b64_e32 v[14:15], v[54:55]
	s_waitcnt vmcnt(23)
	v_mov_b64_e32 v[82:83], v[128:129]
	s_waitcnt vmcnt(22)
	v_mov_b64_e32 v[16:17], v[48:49]
	v_mov_b64_e32 v[18:19], v[50:51]
	s_waitcnt vmcnt(21)
	v_mov_b64_e32 v[88:89], v[138:139]
	s_waitcnt vmcnt(20)
	v_mov_b64_e32 v[86:87], v[130:131]
	s_waitcnt vmcnt(19)
	v_mov_b64_e32 v[92:93], v[136:137]
	s_waitcnt vmcnt(18)
	v_mov_b64_e32 v[98:99], v[146:147]
	s_waitcnt vmcnt(17)
	v_mov_b64_e32 v[96:97], v[140:141]
	s_waitcnt vmcnt(16)
	v_mov_b64_e32 v[100:101], v[144:145]
	s_waitcnt vmcnt(15)
	v_mov_b64_e32 v[106:107], v[148:149]
	s_waitcnt vmcnt(0)
	v_mov_b64_e32 v[38:39], v[6:7]
	v_mov_b64_e32 v[20:21], v[44:45]
	v_mov_b64_e32 v[104:105], v[120:121]
	v_mov_b64_e32 v[24:25], v[40:41]
	v_mov_b64_e32 v[94:95], v[142:143]
	v_mov_b64_e32 v[34:35], v[30:31]
	v_mov_b64_e32 v[102:103], v[150:151]
	v_mov_b64_e32 v[22:23], v[46:47]
	v_mov_b64_e32 v[26:27], v[42:43]
	v_mov_b64_e32 v[32:33], v[28:29]
	v_mov_b64_e32 v[36:37], v[4:5]
	s_branch .LBB0_738
.LBB0_737:
	s_or_b64 exec, exec, s[6:7]
	v_lshlrev_b32_e32 v184, 16, v126
	v_and_b32_e32 v185, 0xffff0000, v126
	v_lshlrev_b32_e32 v186, 16, v127
	v_and_b32_e32 v187, 0xffff0000, v127
	v_lshlrev_b32_e32 v166, 16, v138
	v_and_b32_e32 v167, 0xffff0000, v138
	v_lshlrev_b32_e32 v162, 16, v139
	v_and_b32_e32 v163, 0xffff0000, v139
	v_lshlrev_b32_e32 v160, 16, v130
	v_and_b32_e32 v161, 0xffff0000, v130
	v_lshlrev_b32_e32 v164, 16, v131
	v_and_b32_e32 v165, 0xffff0000, v131
	v_lshlrev_b32_e32 v158, 16, v142
	v_and_b32_e32 v159, 0xffff0000, v142
	v_lshlrev_b32_e32 v154, 16, v143
	v_and_b32_e32 v155, 0xffff0000, v143
	v_lshlrev_b32_e32 v142, 16, v146
	v_and_b32_e32 v143, 0xffff0000, v146
	v_lshlrev_b32_e32 v138, 16, v147
	v_and_b32_e32 v139, 0xffff0000, v147
	v_lshlrev_b32_e32 v126, 16, v144
	v_and_b32_e32 v127, 0xffff0000, v144
	v_lshlrev_b32_e32 v130, 16, v145
	v_and_b32_e32 v131, 0xffff0000, v145
	v_mov_b32_e32 v144, v61
	v_mov_b32_e32 v145, v62
	v_mov_b32_e32 v146, v60
	v_mov_b32_e32 v147, v63
	v_pk_add_f32 v[144:145], v[144:145], v[146:147]
	v_lshlrev_b32_e32 v176, 16, v122
	v_add_f32_e32 v144, v144, v145
	v_and_b32_e32 v177, 0xffff0000, v122
	v_lshlrev_b32_e32 v178, 16, v123
	v_add_f32_dpp v144, v144, v144 quad_perm:[1,0,3,2] row_mask:0xf bank_mask:0xf bound_ctrl:1
	v_and_b32_e32 v179, 0xffff0000, v123
	v_lshlrev_b32_e32 v188, 16, v118
	v_add_f32_dpp v144, v144, v144 quad_perm:[2,3,0,1] row_mask:0xf bank_mask:0xf bound_ctrl:1
	v_and_b32_e32 v189, 0xffff0000, v118
	v_lshlrev_b32_e32 v190, 16, v119
	v_add_f32_dpp v144, v144, v144 row_half_mirror row_mask:0xf bank_mask:0xf bound_ctrl:1
	v_and_b32_e32 v191, 0xffff0000, v119
	v_lshlrev_b32_e32 v122, 16, v148
	v_add_f32_dpp v144, v144, v144 row_mirror row_mask:0xf bank_mask:0xf bound_ctrl:1
	v_fmamk_f32 v61, v144, 0xbc800000, v61
	v_fmamk_f32 v60, v144, 0xbc800000, v60
	v_fmamk_f32 v63, v144, 0xbc800000, v63
	v_fmac_f32_e32 v62, 0xbc800000, v144
	v_pk_mul_f32 v[144:145], v[62:63], v[62:63]
	v_pk_mul_f32 v[146:147], v[60:61], v[60:61]
	v_and_b32_e32 v123, 0xffff0000, v148
	v_lshlrev_b32_e32 v118, 16, v149
	v_and_b32_e32 v119, 0xffff0000, v149
	v_pk_mov_b32 v[148:149], v[146:147], v[144:145] op_sel:[1,0]
	v_mov_b32_e32 v147, v145
	v_pk_add_f32 v[144:145], v[148:149], v[146:147]
	v_lshlrev_b32_e32 v174, 16, v132
	v_add_f32_e32 v144, v144, v145
	v_and_b32_e32 v175, 0xffff0000, v132
	v_lshlrev_b32_e32 v170, 16, v133
	v_add_f32_dpp v144, v144, v144 quad_perm:[1,0,3,2] row_mask:0xf bank_mask:0xf bound_ctrl:1
	v_and_b32_e32 v171, 0xffff0000, v133
	v_lshlrev_b32_e32 v168, 16, v128
	v_add_f32_dpp v144, v144, v144 quad_perm:[2,3,0,1] row_mask:0xf bank_mask:0xf bound_ctrl:1
	v_and_b32_e32 v169, 0xffff0000, v128
	v_lshlrev_b32_e32 v172, 16, v129
	v_add_f32_dpp v144, v144, v144 row_half_mirror row_mask:0xf bank_mask:0xf bound_ctrl:1
	v_and_b32_e32 v173, 0xffff0000, v129
	v_lshlrev_b32_e32 v132, 16, v150
	v_add_f32_dpp v144, v144, v144 row_mirror row_mask:0xf bank_mask:0xf bound_ctrl:1
	v_fmamk_f32 v144, v144, 0x3c800000, v73
	v_mul_f32_e32 v145, 0x4b800000, v144
	v_cmp_gt_f32_e32 vcc, s3, v144
	v_and_b32_e32 v133, 0xffff0000, v150
	v_lshlrev_b32_e32 v128, 16, v151
	v_cndmask_b32_e32 v144, v144, v145, vcc
	v_rsq_f32_e32 v192, v144
	v_and_b32_e32 v129, 0xffff0000, v151
	ds_read_b128 v[144:147], v67
	ds_read_b128 v[148:151], v67 offset:8192
	v_lshlrev_b32_e32 v180, 16, v116
	v_mul_f32_e32 v193, 0x45800000, v192
	v_cndmask_b32_e32 v192, v192, v193, vcc
	v_pk_mul_f32 v[60:61], v[60:61], v[192:193] op_sel_hi:[1,0]
	v_pk_mul_f32 v[62:63], v[62:63], v[192:193] op_sel_hi:[1,0]
	s_waitcnt lgkmcnt(0)
	v_pk_fma_f32 v[60:61], v[144:145], v[60:61], v[148:149]
	v_pk_fma_f32 v[62:63], v[146:147], v[62:63], v[150:151]
	v_and_b32_e32 v181, 0xffff0000, v116
	v_lshlrev_b32_e32 v182, 16, v117
	v_and_b32_e32 v183, 0xffff0000, v117
	s_nop 0
	v_pk_fma_f32 v[60:61], v[134:135], v[176:177], v[60:61] op_sel_hi:[0,1,1]
	v_pk_fma_f32 v[62:63], v[134:135], v[178:179], v[62:63] op_sel_hi:[0,1,1]
	v_pk_mul_f32 v[62:63], v[62:63], v[182:183]
	v_pk_mul_f32 v[60:61], v[60:61], v[180:181]
	v_mov_b32_e32 v144, v56
	v_cvt_pk_bf16_f32 v60, v60, v61
	v_cvt_pk_bf16_f32 v61, v62, v63
	v_mov_b32_e32 v62, v57
	v_mov_b32_e32 v63, v58
	v_mov_b32_e32 v145, v59
	v_pk_add_f32 v[62:63], v[62:63], v[144:145]
	global_store_dwordx2 v[70:71], v[60:61], off
	v_add_f32_e32 v62, v62, v63
	v_lshlrev_b32_e32 v152, 16, v136
	v_and_b32_e32 v153, 0xffff0000, v136
	v_add_f32_dpp v62, v62, v62 quad_perm:[1,0,3,2] row_mask:0xf bank_mask:0xf bound_ctrl:1
	v_lshlrev_b32_e32 v156, 16, v137
	v_and_b32_e32 v157, 0xffff0000, v137
	v_add_f32_dpp v62, v62, v62 quad_perm:[2,3,0,1] row_mask:0xf bank_mask:0xf bound_ctrl:1
	v_lshlrev_b32_e32 v136, 16, v140
	v_and_b32_e32 v137, 0xffff0000, v140
	v_add_f32_dpp v62, v62, v62 row_half_mirror row_mask:0xf bank_mask:0xf bound_ctrl:1
	v_lshlrev_b32_e32 v140, 16, v141
	v_and_b32_e32 v141, 0xffff0000, v141
	v_add_f32_dpp v62, v62, v62 row_mirror row_mask:0xf bank_mask:0xf bound_ctrl:1
	v_fmamk_f32 v57, v62, 0xbc800000, v57
	v_fmamk_f32 v56, v62, 0xbc800000, v56
	v_fmamk_f32 v59, v62, 0xbc800000, v59
	v_fmac_f32_e32 v58, 0xbc800000, v62
	v_pk_mul_f32 v[62:63], v[58:59], v[58:59]
	v_pk_mul_f32 v[144:145], v[56:57], v[56:57]
	v_lshlrev_b32_e32 v116, 16, v120
	v_pk_mov_b32 v[146:147], v[144:145], v[62:63] op_sel:[1,0]
	v_mov_b32_e32 v145, v63
	v_pk_add_f32 v[62:63], v[146:147], v[144:145]
	v_and_b32_e32 v117, 0xffff0000, v120
	v_add_f32_e32 v62, v62, v63
	v_lshlrev_b32_e32 v120, 16, v121
	v_and_b32_e32 v121, 0xffff0000, v121
	v_add_f32_dpp v62, v62, v62 quad_perm:[1,0,3,2] row_mask:0xf bank_mask:0xf bound_ctrl:1
	s_nop 0
	s_nop 0
	v_add_f32_dpp v62, v62, v62 quad_perm:[2,3,0,1] row_mask:0xf bank_mask:0xf bound_ctrl:1
	s_nop 1
	v_add_f32_dpp v62, v62, v62 row_half_mirror row_mask:0xf bank_mask:0xf bound_ctrl:1
	s_nop 1
	v_add_f32_dpp v62, v62, v62 row_mirror row_mask:0xf bank_mask:0xf bound_ctrl:1
	v_fmamk_f32 v62, v62, 0x3c800000, v73
	v_mul_f32_e32 v63, 0x4b800000, v62
	v_cmp_gt_f32_e32 vcc, s3, v62
	s_nop 1
	v_cndmask_b32_e32 v62, v62, v63, vcc
	v_rsq_f32_e32 v134, v62
	ds_read_b128 v[60:63], v67 offset:1024
	ds_read_b128 v[144:147], v67 offset:9216
	v_mul_f32_e32 v148, 0x45800000, v134
	v_cndmask_b32_e32 v134, v134, v148, vcc
	v_pk_mul_f32 v[56:57], v[56:57], v[134:135] op_sel_hi:[1,0]
	v_pk_mul_f32 v[58:59], v[58:59], v[134:135] op_sel_hi:[1,0]
	s_waitcnt lgkmcnt(0)
	v_pk_fma_f32 v[56:57], v[60:61], v[56:57], v[144:145]
	v_pk_fma_f32 v[58:59], v[62:63], v[58:59], v[146:147]
	v_pk_fma_f32 v[56:57], v[124:125], v[184:185], v[56:57] op_sel_hi:[0,1,1]
	v_pk_fma_f32 v[58:59], v[124:125], v[186:187], v[58:59] op_sel_hi:[0,1,1]
	v_pk_mul_f32 v[58:59], v[58:59], v[190:191]
	v_pk_mul_f32 v[56:57], v[56:57], v[188:189]
	v_mov_b32_e32 v60, v52
	v_cvt_pk_bf16_f32 v56, v56, v57
	v_cvt_pk_bf16_f32 v57, v58, v59
	v_mov_b32_e32 v58, v53
	v_mov_b32_e32 v59, v54
	v_mov_b32_e32 v61, v55
	v_pk_add_f32 v[58:59], v[58:59], v[60:61]
	global_store_dwordx2 v[70:71], v[56:57], off offset:512
	v_add_f32_e32 v58, v58, v59
	s_nop 0
	s_nop 0
	v_add_f32_dpp v58, v58, v58 quad_perm:[1,0,3,2] row_mask:0xf bank_mask:0xf bound_ctrl:1
	s_nop 0
	s_nop 0
	v_add_f32_dpp v58, v58, v58 quad_perm:[2,3,0,1] row_mask:0xf bank_mask:0xf bound_ctrl:1
	s_nop 1
	v_add_f32_dpp v58, v58, v58 row_half_mirror row_mask:0xf bank_mask:0xf bound_ctrl:1
	s_nop 1
	v_add_f32_dpp v58, v58, v58 row_mirror row_mask:0xf bank_mask:0xf bound_ctrl:1
	v_fmamk_f32 v53, v58, 0xbc800000, v53
	v_fmamk_f32 v52, v58, 0xbc800000, v52
	v_fmamk_f32 v55, v58, 0xbc800000, v55
	v_fmac_f32_e32 v54, 0xbc800000, v58
	v_pk_mul_f32 v[58:59], v[54:55], v[54:55]
	v_pk_mul_f32 v[60:61], v[52:53], v[52:53]
	s_nop 0
	v_pk_mov_b32 v[62:63], v[60:61], v[58:59] op_sel:[1,0]
	v_mov_b32_e32 v61, v59
	v_pk_add_f32 v[58:59], v[62:63], v[60:61]
	s_nop 0
	v_add_f32_e32 v58, v58, v59
	s_nop 1
	v_add_f32_dpp v58, v58, v58 quad_perm:[1,0,3,2] row_mask:0xf bank_mask:0xf bound_ctrl:1
	s_nop 1
	v_add_f32_dpp v58, v58, v58 quad_perm:[2,3,0,1] row_mask:0xf bank_mask:0xf bound_ctrl:1
	s_nop 1
	v_add_f32_dpp v58, v58, v58 row_half_mirror row_mask:0xf bank_mask:0xf bound_ctrl:1
	s_nop 1
	v_add_f32_dpp v58, v58, v58 row_mirror row_mask:0xf bank_mask:0xf bound_ctrl:1
	v_fmamk_f32 v58, v58, 0x3c800000, v73
	v_mul_f32_e32 v59, 0x4b800000, v58
	v_cmp_gt_f32_e32 vcc, s3, v58
	s_nop 1
	v_cndmask_b32_e32 v58, v58, v59, vcc
	v_rsq_f32_e32 v124, v58
	ds_read_b128 v[56:59], v67 offset:2048
	ds_read_b128 v[60:63], v67 offset:10240
	v_mul_f32_e32 v134, 0x45800000, v124
	v_cndmask_b32_e32 v124, v124, v134, vcc
	v_pk_mul_f32 v[52:53], v[52:53], v[124:125] op_sel_hi:[1,0]
	v_pk_mul_f32 v[54:55], v[54:55], v[124:125] op_sel_hi:[1,0]
	s_waitcnt lgkmcnt(0)
	v_pk_fma_f32 v[52:53], v[56:57], v[52:53], v[60:61]
	v_pk_fma_f32 v[54:55], v[58:59], v[54:55], v[62:63]
	v_pk_fma_f32 v[52:53], v[114:115], v[174:175], v[52:53] op_sel_hi:[0,1,1]
	v_pk_fma_f32 v[54:55], v[114:115], v[170:171], v[54:55] op_sel_hi:[0,1,1]
	v_pk_mul_f32 v[54:55], v[54:55], v[172:173]
	v_pk_mul_f32 v[52:53], v[52:53], v[168:169]
	v_mov_b32_e32 v56, v48
	v_cvt_pk_bf16_f32 v52, v52, v53
	v_cvt_pk_bf16_f32 v53, v54, v55
	v_mov_b32_e32 v54, v49
	v_mov_b32_e32 v55, v50
	v_mov_b32_e32 v57, v51
	v_pk_add_f32 v[54:55], v[54:55], v[56:57]
	global_store_dwordx2 v[70:71], v[52:53], off offset:1024
	v_add_f32_e32 v54, v54, v55
	s_nop 0
	s_nop 0
	v_add_f32_dpp v54, v54, v54 quad_perm:[1,0,3,2] row_mask:0xf bank_mask:0xf bound_ctrl:1
	s_nop 0
	s_nop 0
	v_add_f32_dpp v54, v54, v54 quad_perm:[2,3,0,1] row_mask:0xf bank_mask:0xf bound_ctrl:1
	s_nop 1
	v_add_f32_dpp v54, v54, v54 row_half_mirror row_mask:0xf bank_mask:0xf bound_ctrl:1
	s_nop 1
	v_add_f32_dpp v54, v54, v54 row_mirror row_mask:0xf bank_mask:0xf bound_ctrl:1
	v_fmamk_f32 v49, v54, 0xbc800000, v49
	v_fmamk_f32 v48, v54, 0xbc800000, v48
	v_fmamk_f32 v51, v54, 0xbc800000, v51
	v_fmac_f32_e32 v50, 0xbc800000, v54
	v_pk_mul_f32 v[54:55], v[50:51], v[50:51]
	v_pk_mul_f32 v[56:57], v[48:49], v[48:49]
	s_nop 0
	v_pk_mov_b32 v[58:59], v[56:57], v[54:55] op_sel:[1,0]
	v_mov_b32_e32 v57, v55
	v_pk_add_f32 v[54:55], v[58:59], v[56:57]
	s_nop 0
	v_add_f32_e32 v54, v54, v55
	s_nop 1
	v_add_f32_dpp v54, v54, v54 quad_perm:[1,0,3,2] row_mask:0xf bank_mask:0xf bound_ctrl:1
	s_nop 1
	v_add_f32_dpp v54, v54, v54 quad_perm:[2,3,0,1] row_mask:0xf bank_mask:0xf bound_ctrl:1
	s_nop 1
	v_add_f32_dpp v54, v54, v54 row_half_mirror row_mask:0xf bank_mask:0xf bound_ctrl:1
	s_nop 1
	v_add_f32_dpp v54, v54, v54 row_mirror row_mask:0xf bank_mask:0xf bound_ctrl:1
	v_fmamk_f32 v54, v54, 0x3c800000, v73
	v_mul_f32_e32 v55, 0x4b800000, v54
	v_cmp_gt_f32_e32 vcc, s3, v54
	s_nop 1
	v_cndmask_b32_e32 v54, v54, v55, vcc
	v_rsq_f32_e32 v60, v54
	ds_read_b128 v[52:55], v67 offset:3072
	ds_read_b128 v[56:59], v67 offset:11264
	v_mul_f32_e32 v61, 0x45800000, v60
	v_cndmask_b32_e32 v60, v60, v61, vcc
	v_pk_mul_f32 v[48:49], v[48:49], v[60:61] op_sel_hi:[1,0]
	v_pk_mul_f32 v[50:51], v[50:51], v[60:61] op_sel_hi:[1,0]
	s_waitcnt lgkmcnt(0)
	v_pk_fma_f32 v[48:49], v[52:53], v[48:49], v[56:57]
	v_pk_fma_f32 v[50:51], v[54:55], v[50:51], v[58:59]
	v_pk_fma_f32 v[48:49], v[112:113], v[166:167], v[48:49] op_sel_hi:[0,1,1]
	v_pk_fma_f32 v[50:51], v[112:113], v[162:163], v[50:51] op_sel_hi:[0,1,1]
	v_pk_mul_f32 v[50:51], v[50:51], v[164:165]
	v_pk_mul_f32 v[48:49], v[48:49], v[160:161]
	v_mov_b32_e32 v52, v44
	v_cvt_pk_bf16_f32 v48, v48, v49
	v_cvt_pk_bf16_f32 v49, v50, v51
	v_mov_b32_e32 v50, v45
	v_mov_b32_e32 v51, v46
	v_mov_b32_e32 v53, v47
	v_pk_add_f32 v[50:51], v[50:51], v[52:53]
	global_store_dwordx2 v[70:71], v[48:49], off offset:1536
	v_add_f32_e32 v50, v50, v51
	s_nop 0
	s_nop 0
	v_add_f32_dpp v50, v50, v50 quad_perm:[1,0,3,2] row_mask:0xf bank_mask:0xf bound_ctrl:1
	s_nop 0
	s_nop 0
	v_add_f32_dpp v50, v50, v50 quad_perm:[2,3,0,1] row_mask:0xf bank_mask:0xf bound_ctrl:1
	s_nop 1
	v_add_f32_dpp v50, v50, v50 row_half_mirror row_mask:0xf bank_mask:0xf bound_ctrl:1
	s_nop 1
	v_add_f32_dpp v50, v50, v50 row_mirror row_mask:0xf bank_mask:0xf bound_ctrl:1
	v_fmamk_f32 v45, v50, 0xbc800000, v45
	v_fmamk_f32 v44, v50, 0xbc800000, v44
	v_fmamk_f32 v47, v50, 0xbc800000, v47
	v_fmac_f32_e32 v46, 0xbc800000, v50
	v_pk_mul_f32 v[50:51], v[46:47], v[46:47]
	v_pk_mul_f32 v[52:53], v[44:45], v[44:45]
	s_nop 0
	v_pk_mov_b32 v[54:55], v[52:53], v[50:51] op_sel:[1,0]
	v_mov_b32_e32 v53, v51
	v_pk_add_f32 v[50:51], v[54:55], v[52:53]
	s_nop 0
	v_add_f32_e32 v50, v50, v51
	s_nop 1
	v_add_f32_dpp v50, v50, v50 quad_perm:[1,0,3,2] row_mask:0xf bank_mask:0xf bound_ctrl:1
	s_nop 1
	v_add_f32_dpp v50, v50, v50 quad_perm:[2,3,0,1] row_mask:0xf bank_mask:0xf bound_ctrl:1
	s_nop 1
	v_add_f32_dpp v50, v50, v50 row_half_mirror row_mask:0xf bank_mask:0xf bound_ctrl:1
	s_nop 1
	v_add_f32_dpp v50, v50, v50 row_mirror row_mask:0xf bank_mask:0xf bound_ctrl:1
	v_fmamk_f32 v50, v50, 0x3c800000, v73
	v_mul_f32_e32 v51, 0x4b800000, v50
	v_cmp_gt_f32_e32 vcc, s3, v50
	s_nop 1
	v_cndmask_b32_e32 v50, v50, v51, vcc
	v_rsq_f32_e32 v56, v50
	ds_read_b128 v[48:51], v67 offset:4096
	ds_read_b128 v[52:55], v67 offset:12288
	v_mul_f32_e32 v57, 0x45800000, v56
	v_cndmask_b32_e32 v56, v56, v57, vcc
	v_pk_mul_f32 v[44:45], v[44:45], v[56:57] op_sel_hi:[1,0]
	v_pk_mul_f32 v[46:47], v[46:47], v[56:57] op_sel_hi:[1,0]
	s_waitcnt lgkmcnt(0)
	v_pk_fma_f32 v[44:45], v[48:49], v[44:45], v[52:53]
	v_pk_fma_f32 v[46:47], v[50:51], v[46:47], v[54:55]
	v_pk_fma_f32 v[44:45], v[110:111], v[158:159], v[44:45] op_sel_hi:[0,1,1]
	v_pk_fma_f32 v[46:47], v[110:111], v[154:155], v[46:47] op_sel_hi:[0,1,1]
	v_pk_mul_f32 v[46:47], v[46:47], v[156:157]
	v_pk_mul_f32 v[44:45], v[44:45], v[152:153]
	v_mov_b32_e32 v48, v40
	v_cvt_pk_bf16_f32 v44, v44, v45
	v_cvt_pk_bf16_f32 v45, v46, v47
	v_mov_b32_e32 v46, v41
	v_mov_b32_e32 v47, v42
	v_mov_b32_e32 v49, v43
	v_pk_add_f32 v[46:47], v[46:47], v[48:49]
	global_store_dwordx2 v[70:71], v[44:45], off offset:2048
	v_add_f32_e32 v46, v46, v47
	s_nop 0
	s_nop 0
	v_add_f32_dpp v46, v46, v46 quad_perm:[1,0,3,2] row_mask:0xf bank_mask:0xf bound_ctrl:1
	s_nop 0
	s_nop 0
	v_add_f32_dpp v46, v46, v46 quad_perm:[2,3,0,1] row_mask:0xf bank_mask:0xf bound_ctrl:1
	s_nop 1
	v_add_f32_dpp v46, v46, v46 row_half_mirror row_mask:0xf bank_mask:0xf bound_ctrl:1
	s_nop 1
	v_add_f32_dpp v46, v46, v46 row_mirror row_mask:0xf bank_mask:0xf bound_ctrl:1
	v_fmamk_f32 v41, v46, 0xbc800000, v41
	v_fmamk_f32 v40, v46, 0xbc800000, v40
	v_fmamk_f32 v43, v46, 0xbc800000, v43
	v_fmac_f32_e32 v42, 0xbc800000, v46
	v_pk_mul_f32 v[46:47], v[42:43], v[42:43]
	v_pk_mul_f32 v[48:49], v[40:41], v[40:41]
	s_nop 0
	v_pk_mov_b32 v[50:51], v[48:49], v[46:47] op_sel:[1,0]
	v_mov_b32_e32 v49, v47
	v_pk_add_f32 v[46:47], v[50:51], v[48:49]
	s_nop 0
	v_add_f32_e32 v46, v46, v47
	s_nop 1
	v_add_f32_dpp v46, v46, v46 quad_perm:[1,0,3,2] row_mask:0xf bank_mask:0xf bound_ctrl:1
	s_nop 1
	v_add_f32_dpp v46, v46, v46 quad_perm:[2,3,0,1] row_mask:0xf bank_mask:0xf bound_ctrl:1
	s_nop 1
	v_add_f32_dpp v46, v46, v46 row_half_mirror row_mask:0xf bank_mask:0xf bound_ctrl:1
	s_nop 1
	v_add_f32_dpp v46, v46, v46 row_mirror row_mask:0xf bank_mask:0xf bound_ctrl:1
	v_fmamk_f32 v46, v46, 0x3c800000, v73
	v_mul_f32_e32 v47, 0x4b800000, v46
	v_cmp_gt_f32_e32 vcc, s3, v46
	s_nop 1
	v_cndmask_b32_e32 v46, v46, v47, vcc
	v_rsq_f32_e32 v52, v46
	ds_read_b128 v[44:47], v67 offset:5120
	ds_read_b128 v[48:51], v67 offset:13312
	v_mul_f32_e32 v53, 0x45800000, v52
	v_cndmask_b32_e32 v52, v52, v53, vcc
	v_pk_mul_f32 v[40:41], v[40:41], v[52:53] op_sel_hi:[1,0]
	v_pk_mul_f32 v[42:43], v[42:43], v[52:53] op_sel_hi:[1,0]
	s_waitcnt lgkmcnt(0)
	v_pk_fma_f32 v[40:41], v[44:45], v[40:41], v[48:49]
	v_pk_fma_f32 v[42:43], v[46:47], v[42:43], v[50:51]
	v_pk_fma_f32 v[40:41], v[108:109], v[142:143], v[40:41] op_sel_hi:[0,1,1]
	v_pk_fma_f32 v[42:43], v[108:109], v[138:139], v[42:43] op_sel_hi:[0,1,1]
	v_pk_mul_f32 v[42:43], v[42:43], v[140:141]
	v_pk_mul_f32 v[40:41], v[40:41], v[136:137]
	v_mov_b32_e32 v44, v28
	v_cvt_pk_bf16_f32 v40, v40, v41
	v_cvt_pk_bf16_f32 v41, v42, v43
	v_mov_b32_e32 v42, v29
	v_mov_b32_e32 v43, v30
	v_mov_b32_e32 v45, v31
	v_pk_add_f32 v[42:43], v[42:43], v[44:45]
	global_store_dwordx2 v[70:71], v[40:41], off offset:2560
	v_add_f32_e32 v42, v42, v43
	s_nop 0
	s_nop 0
	v_add_f32_dpp v42, v42, v42 quad_perm:[1,0,3,2] row_mask:0xf bank_mask:0xf bound_ctrl:1
	s_nop 0
	s_nop 0
	v_add_f32_dpp v42, v42, v42 quad_perm:[2,3,0,1] row_mask:0xf bank_mask:0xf bound_ctrl:1
	s_nop 0
	s_nop 0
	v_add_f32_dpp v42, v42, v42 row_half_mirror row_mask:0xf bank_mask:0xf bound_ctrl:1
	s_nop 0
	s_nop 0
	v_add_f32_dpp v42, v42, v42 row_mirror row_mask:0xf bank_mask:0xf bound_ctrl:1
	v_fmamk_f32 v29, v42, 0xbc800000, v29
	v_fmamk_f32 v28, v42, 0xbc800000, v28
	v_fmamk_f32 v31, v42, 0xbc800000, v31
	v_fmac_f32_e32 v30, 0xbc800000, v42
	v_pk_mul_f32 v[42:43], v[30:31], v[30:31]
	v_pk_mul_f32 v[44:45], v[28:29], v[28:29]
	s_nop 0
	v_pk_mov_b32 v[46:47], v[44:45], v[42:43] op_sel:[1,0]
	v_mov_b32_e32 v45, v43
	v_pk_add_f32 v[42:43], v[46:47], v[44:45]
	s_nop 0
	v_add_f32_e32 v42, v42, v43
	s_nop 1
	v_add_f32_dpp v42, v42, v42 quad_perm:[1,0,3,2] row_mask:0xf bank_mask:0xf bound_ctrl:1
	s_nop 1
	v_add_f32_dpp v42, v42, v42 quad_perm:[2,3,0,1] row_mask:0xf bank_mask:0xf bound_ctrl:1
	s_nop 1
	v_add_f32_dpp v42, v42, v42 row_half_mirror row_mask:0xf bank_mask:0xf bound_ctrl:1
	s_nop 1
	v_add_f32_dpp v42, v42, v42 row_mirror row_mask:0xf bank_mask:0xf bound_ctrl:1
	v_fmamk_f32 v42, v42, 0x3c800000, v73
	v_mul_f32_e32 v43, 0x4b800000, v42
	v_cmp_gt_f32_e32 vcc, s3, v42
	s_nop 1
	v_cndmask_b32_e32 v42, v42, v43, vcc
	v_rsq_f32_e32 v48, v42
	ds_read_b128 v[40:43], v67 offset:6144
	ds_read_b128 v[44:47], v67 offset:14336
	v_mul_f32_e32 v49, 0x45800000, v48
	v_cndmask_b32_e32 v48, v48, v49, vcc
	v_pk_mul_f32 v[28:29], v[28:29], v[48:49] op_sel_hi:[1,0]
	v_pk_mul_f32 v[30:31], v[30:31], v[48:49] op_sel_hi:[1,0]
	s_waitcnt lgkmcnt(0)
	v_pk_fma_f32 v[28:29], v[40:41], v[28:29], v[44:45]
	v_pk_fma_f32 v[30:31], v[42:43], v[30:31], v[46:47]
	v_pk_fma_f32 v[28:29], v[90:91], v[132:133], v[28:29] op_sel_hi:[0,1,1]
	v_pk_fma_f32 v[30:31], v[90:91], v[128:129], v[30:31] op_sel_hi:[0,1,1]
	v_pk_mul_f32 v[30:31], v[30:31], v[130:131]
	v_pk_mul_f32 v[28:29], v[28:29], v[126:127]
	v_mov_b32_e32 v40, v4
	v_cvt_pk_bf16_f32 v28, v28, v29
	v_cvt_pk_bf16_f32 v29, v30, v31
	v_mov_b32_e32 v30, v5
	v_mov_b32_e32 v31, v6
	v_mov_b32_e32 v41, v7
	v_pk_add_f32 v[30:31], v[30:31], v[40:41]
	global_store_dwordx2 v[70:71], v[28:29], off offset:3072
	v_add_f32_e32 v30, v30, v31
	s_nop 0
	s_nop 0
	v_add_f32_dpp v30, v30, v30 quad_perm:[1,0,3,2] row_mask:0xf bank_mask:0xf bound_ctrl:1
	s_nop 0
	s_nop 0
	v_add_f32_dpp v30, v30, v30 quad_perm:[2,3,0,1] row_mask:0xf bank_mask:0xf bound_ctrl:1
	s_nop 0
	s_nop 0
	v_add_f32_dpp v30, v30, v30 row_half_mirror row_mask:0xf bank_mask:0xf bound_ctrl:1
	s_nop 0
	s_nop 0
	v_add_f32_dpp v30, v30, v30 row_mirror row_mask:0xf bank_mask:0xf bound_ctrl:1
	v_fmamk_f32 v5, v30, 0xbc800000, v5
	v_fmamk_f32 v4, v30, 0xbc800000, v4
	v_fmamk_f32 v7, v30, 0xbc800000, v7
	v_fmac_f32_e32 v6, 0xbc800000, v30
	v_pk_mul_f32 v[30:31], v[6:7], v[6:7]
	v_pk_mul_f32 v[40:41], v[4:5], v[4:5]
	s_nop 0
	v_pk_mov_b32 v[42:43], v[40:41], v[30:31] op_sel:[1,0]
	v_mov_b32_e32 v41, v31
	v_pk_add_f32 v[30:31], v[42:43], v[40:41]
	s_nop 0
	v_add_f32_e32 v30, v30, v31
	s_nop 1
	v_add_f32_dpp v30, v30, v30 quad_perm:[1,0,3,2] row_mask:0xf bank_mask:0xf bound_ctrl:1
	s_nop 1
	v_add_f32_dpp v30, v30, v30 quad_perm:[2,3,0,1] row_mask:0xf bank_mask:0xf bound_ctrl:1
	s_nop 1
	v_add_f32_dpp v30, v30, v30 row_half_mirror row_mask:0xf bank_mask:0xf bound_ctrl:1
	s_nop 1
	v_add_f32_dpp v30, v30, v30 row_mirror row_mask:0xf bank_mask:0xf bound_ctrl:1
	v_fmamk_f32 v30, v30, 0x3c800000, v73
	v_mul_f32_e32 v31, 0x4b800000, v30
	v_cmp_gt_f32_e32 vcc, s3, v30
	s_nop 1
	v_cndmask_b32_e32 v30, v30, v31, vcc
	v_rsq_f32_e32 v44, v30
	ds_read_b128 v[28:31], v67 offset:7168
	ds_read_b128 v[40:43], v67 offset:15360
	v_mul_f32_e32 v45, 0x45800000, v44
	v_cndmask_b32_e32 v44, v44, v45, vcc
	v_pk_mul_f32 v[4:5], v[4:5], v[44:45] op_sel_hi:[1,0]
	v_pk_mul_f32 v[6:7], v[6:7], v[44:45] op_sel_hi:[1,0]
	s_waitcnt lgkmcnt(0)
	v_pk_fma_f32 v[4:5], v[28:29], v[4:5], v[40:41]
	v_pk_fma_f32 v[6:7], v[30:31], v[6:7], v[42:43]
	v_pk_fma_f32 v[4:5], v[72:73], v[122:123], v[4:5] op_sel_hi:[0,1,1]
	v_pk_fma_f32 v[6:7], v[72:73], v[118:119], v[6:7] op_sel_hi:[0,1,1]
	v_pk_mul_f32 v[4:5], v[4:5], v[116:117]
	v_pk_mul_f32 v[6:7], v[6:7], v[120:121]
	v_cvt_pk_bf16_f32 v4, v4, v5
	s_nop 0
	v_cvt_pk_bf16_f32 v5, v6, v7
	global_store_dwordx2 v[70:71], v[4:5], off offset:3584
	s_waitcnt vmcnt(8)
	v_mov_b64_e32 v[150:151], v[102:103]
	v_mov_b64_e32 v[144:145], v[100:101]
	v_mov_b64_e32 v[146:147], v[98:99]
	v_mov_b64_e32 v[148:149], v[106:107]
	v_mov_b32_e32 v114, v109
	v_mov_b32_e32 v124, v91
	v_mov_b32_e32 v134, v65
	v_mov_b64_e32 v[62:63], v[2:3]
	v_mov_b32_e32 v112, v111
	v_mov_b64_e32 v[60:61], v[0:1]
	v_mov_b64_e32 v[58:59], v[10:11]
	v_mov_b32_e32 v110, v113
	v_mov_b64_e32 v[56:57], v[8:9]
	v_mov_b64_e32 v[54:55], v[14:15]
	v_mov_b32_e32 v108, v115
	v_mov_b64_e32 v[136:137], v[92:93]
	v_mov_b64_e32 v[140:141], v[96:97]
	v_mov_b64_e32 v[138:139], v[88:89]
	v_mov_b64_e32 v[142:143], v[94:95]
	v_mov_b64_e32 v[52:53], v[12:13]
	v_mov_b64_e32 v[50:51], v[18:19]
	v_mov_b32_e32 v90, v125
	v_mov_b64_e32 v[128:129], v[82:83]
	v_mov_b64_e32 v[130:131], v[86:87]
	v_mov_b64_e32 v[126:127], v[80:81]
	v_mov_b64_e32 v[132:133], v[84:85]
	v_mov_b64_e32 v[48:49], v[16:17]
	v_mov_b64_e32 v[46:47], v[22:23]
	v_mov_b64_e32 v[42:43], v[26:27]
	v_mov_b64_e32 v[28:29], v[32:33]
	v_mov_b64_e32 v[4:5], v[36:37]
	v_lshl_add_u64 v[70:71], v[70:71], 0, s[14:15]
	v_mov_b32_e32 v72, v135
	v_mov_b64_e32 v[116:117], v[74:75]
	v_mov_b64_e32 v[118:119], v[78:79]
	v_mov_b64_e32 v[120:121], v[104:105]
	v_mov_b64_e32 v[122:123], v[76:77]
	v_mov_b64_e32 v[44:45], v[20:21]
	v_mov_b64_e32 v[40:41], v[24:25]
	v_mov_b64_e32 v[30:31], v[34:35]
	v_mov_b64_e32 v[6:7], v[38:39]
	s_andn2_b64 exec, exec, s[16:17]
	s_cbranch_execz .LBB0_740
.LBB0_738:
	v_add_u32_e32 v64, s42, v64
	v_cmp_lt_i32_e64 s[6:7], s1, v64
	v_cmp_gt_i32_e32 vcc, s0, v64
	s_or_b64 s[16:17], s[6:7], s[16:17]
	s_nop 0
	v_mov_b32_e32 v135, v72
	v_mov_b32_e32 v125, v90
	v_mov_b32_e32 v115, v108
	v_mov_b32_e32 v113, v110
	v_mov_b32_e32 v111, v112
	v_mov_b32_e32 v109, v114
	v_mov_b32_e32 v91, v124
	v_mov_b32_e32 v65, v134
	s_and_saveexec_b64 s[6:7], vcc
	s_cbranch_execz .LBB0_737
	v_ashrrev_i32_e32 v65, 31, v64
	v_lshlrev_b64 v[104:105], 11, v[64:65]
	v_or_b32_e32 v104, v104, v66
	v_lshlrev_b64 v[0:1], 7, v[64:65]
	v_lshlrev_b64 v[8:9], 1, v[104:105]
	v_lshl_add_u64 v[152:153], v[68:69], 0, v[0:1]
	v_lshl_add_u64 v[0:1], v[104:105], 2, s[8:9]
	v_lshl_add_u64 v[10:11], s[10:11], 0, v[8:9]
	v_or_b32_e32 v12, 0x100, v104
	v_mov_b32_e32 v13, v105
	global_load_dwordx4 v[0:3], v[0:1], off
	s_nop 0
	global_load_dwordx2 v[76:77], v[10:11], off
	v_lshl_add_u64 v[10:11], v[12:13], 2, s[8:9]
	v_lshlrev_b64 v[12:13], 1, v[12:13]
	v_lshl_add_u64 v[8:9], s[12:13], 0, v[8:9]
	v_lshl_add_u64 v[14:15], s[10:11], 0, v[12:13]
	v_lshl_add_u64 v[12:13], s[12:13], 0, v[12:13]
	global_load_dwordx2 v[74:75], v[8:9], off
	s_nop 0
	global_load_dwordx4 v[8:11], v[10:11], off
	s_nop 0
	global_load_dwordx2 v[80:81], v[14:15], off
	global_load_dwordx2 v[78:79], v[12:13], off
	v_or_b32_e32 v12, 0x200, v104
	v_mov_b32_e32 v13, v105
	v_lshlrev_b64 v[16:17], 1, v[12:13]
	v_lshl_add_u64 v[14:15], v[12:13], 2, s[8:9]
	v_lshl_add_u64 v[18:19], s[10:11], 0, v[16:17]
	v_or_b32_e32 v20, 0x300, v104
	v_mov_b32_e32 v21, v105
	global_load_dwordx4 v[12:15], v[14:15], off
	s_nop 0
	global_load_dwordx2 v[84:85], v[18:19], off
	v_lshl_add_u64 v[18:19], v[20:21], 2, s[8:9]
	v_lshlrev_b64 v[20:21], 1, v[20:21]
	v_lshl_add_u64 v[16:17], s[12:13], 0, v[16:17]
	v_lshl_add_u64 v[22:23], s[10:11], 0, v[20:21]
	v_lshl_add_u64 v[20:21], s[12:13], 0, v[20:21]
	global_load_dwordx2 v[82:83], v[16:17], off
	s_nop 0
	global_load_dwordx4 v[16:19], v[18:19], off
	s_nop 0
	global_load_dwordx2 v[88:89], v[22:23], off
	global_load_dwordx2 v[86:87], v[20:21], off
	v_or_b32_e32 v20, 0x400, v104
	v_mov_b32_e32 v21, v105
	v_lshlrev_b64 v[24:25], 1, v[20:21]
	v_lshl_add_u64 v[22:23], v[20:21], 2, s[8:9]
	v_lshl_add_u64 v[26:27], s[10:11], 0, v[24:25]
	v_or_b32_e32 v32, 0x500, v104
	v_mov_b32_e32 v33, v105
	global_load_dwordx4 v[20:23], v[22:23], off
	s_nop 0
	global_load_dwordx2 v[94:95], v[26:27], off
	v_lshl_add_u64 v[26:27], v[32:33], 2, s[8:9]
	v_lshlrev_b64 v[32:33], 1, v[32:33]
	v_lshl_add_u64 v[24:25], s[12:13], 0, v[24:25]
	v_lshl_add_u64 v[34:35], s[10:11], 0, v[32:33]
	v_lshl_add_u64 v[32:33], s[12:13], 0, v[32:33]
	global_load_dwordx2 v[92:93], v[24:25], off
	s_nop 0
	global_load_dwordx4 v[24:27], v[26:27], off
	s_nop 0
	global_load_dwordx2 v[98:99], v[34:35], off
	global_load_dwordx2 v[96:97], v[32:33], off
	v_or_b32_e32 v32, 0x600, v104
	v_mov_b32_e32 v33, v105
	v_lshlrev_b64 v[36:37], 1, v[32:33]
	v_lshl_add_u64 v[34:35], v[32:33], 2, s[8:9]
	v_lshl_add_u64 v[38:39], s[10:11], 0, v[36:37]
	v_or_b32_e32 v104, 0x700, v104
	global_load_dwordx4 v[32:35], v[34:35], off
	s_nop 0
	global_load_dwordx2 v[102:103], v[38:39], off
	v_lshl_add_u64 v[38:39], v[104:105], 2, s[8:9]
	v_lshlrev_b64 v[104:105], 1, v[104:105]
	v_lshl_add_u64 v[36:37], s[12:13], 0, v[36:37]
	v_lshl_add_u64 v[106:107], s[10:11], 0, v[104:105]
	v_lshl_add_u64 v[104:105], s[12:13], 0, v[104:105]
	global_load_dwordx2 v[100:101], v[36:37], off
	s_nop 0
	global_load_dwordx4 v[36:39], v[38:39], off
	s_nop 0
	global_load_dwordx2 v[106:107], v[106:107], off
	s_nop 0
	global_load_dwordx2 v[104:105], v[104:105], off
	s_nop 0
	global_load_dword v65, v[152:153], off
	global_load_dword v91, v[152:153], off offset:16
	global_load_dword v109, v[152:153], off offset:32
	global_load_dword v111, v[152:153], off offset:48
	global_load_dword v113, v[152:153], off offset:64
	global_load_dword v115, v[152:153], off offset:80
	global_load_dword v125, v[152:153], off offset:96
	global_load_dword v135, v[152:153], off offset:112
	s_branch .LBB0_737
